# speedup vs baseline: 1.0160x; 1.0160x over previous
; DI unsigned pk2(float lo, float hi) { const f32x2 v = {lo, hi}; const bf16x2_t b = __builtin_convertvector(v, bf16x2_t); return __builtin_bit_cast(unsigned, b); }
; DI f32x4 ldbf4(const u16* p) { const u32x2 v = *(const u32x2*)p; return (f32x4){bf2f(v.x & 0xffffu), bf2f(v.x >> 16), bf2f(v.y & 0xffffu), bf2f(v.y >> 16)}; }
; #define ROW_ALLSUM4(v) do { v += DPPF4(v, 0x128); v += DPPF4(v, 0x124); v += DPPF4(v, 0x122); v += DPPF4(v, 0x121); } while (0)
; __global__ void __launch_bounds__(512, 2) fwd_megakernel(Args a) {
;     ...
;         for (int it = gw; it < M * NH / 4; it += NGW) {
;             const int mh = it * 4 + (lane >> 4), m = mh >> 4, h = mh & 15, c = h * 64 + 4 * (lane & 15);
;             const f32x4 y = *(const f32x4*)(yraw + (size_t)m * RW + c);
;             float sm = (y.x + y.y) + (y.z + y.w); ROW_ALLSUM4(sm);
;             const float mu = sm * (1.f / 64.f); const f32x4 d = y - mu;
;             float sq = (d.x * d.x + d.y * d.y) + (d.z * d.z + d.w * d.w); ROW_ALLSUM4(sq);
;             const f32x4 yn = d * __builtin_amdgcn_rsqf(sq * (1.f / 64.f) + GN_EPS) * *(const f32x4*)(gn_w + c) + *(const f32x4*)(gn_b + c);
;             const f32x4 v = ldbf4(P + (size_t)m * RPROJ + 2048 + c);
;             const f32x4 vp = ((m & (SEQ - 1)) != 0) ? ldbf4(P + (size_t)(m - 1) * RPROJ + 2048 + c) : (f32x4){0.f, 0.f, 0.f, 0.f};
;             const f32x4 vs = v + (vp - v) * *(const f32x4*)(shift_mix + 2048 + c);
;             u32x2* p = (u32x2*)(SG + (size_t)m * 2048 + c); const u32x2 g2 = *p;
;             const f32x4 o = (yn + bonus[(size_t)m * NH + h] * vs) * (f32x4){bf2f(g2.x & 0xffffu), bf2f(g2.x >> 16), bf2f(g2.y & 0xffffu), bf2f(g2.y >> 16)};
;             u32x2 w; w.x = pk2(o.x, o.y); w.y = pk2(o.z, o.w); *p = w;
.LBB0_533:
	s_or_b64 exec, exec, s[0:1]
	s_cmpk_gt_i32 s92, 0x7fff
	s_waitcnt lgkmcnt(0)
	s_barrier
	s_cbranch_scc1 .LBB0_538
	v_readlane_b32 s0, v252, 14
	v_mov_b32_e32 v76, 0x3a27c5ac
	s_nop 3
	s_and_b32 s0, s0, 3
	s_lshl_b32 s0, s0, 2
	v_or_b32_e32 v62, s0, v202
	v_lshl_or_b32 v60, v62, 6, v164
	v_lshlrev_b32_e32 v61, 1, v60
	v_lshlrev_b32_e32 v60, 2, v60
	v_lshlrev_b32_e32 v62, 2, v62
	s_add_u32 s0, s48, 0x2000
	s_addc_u32 s1, s49, 0
	global_load_dwordx4 v[64:67], v60, s[80:81]
	global_load_dwordx4 v[68:71], v60, s[82:83]
	global_load_dwordx4 v[72:75], v60, s[0:1]
	s_mov_b32 s12, s92
	s_ashr_i32 s0, s12, 2
	s_lshl_b32 s1, s0, 12
	s_add_u32 s2, s88, 0x7b00000
	s_addc_u32 s3, s89, 0
	s_add_u32 s2, s2, s1
	s_addc_u32 s3, s3, 0
	s_add_u32 s8, s60, s1
	s_addc_u32 s9, s61, 0
	s_mul_i32 s1, s0, 0x1800
	s_add_u32 s4, s50, s1
	s_addc_u32 s5, s51, 0
	s_add_u32 s4, s4, 0x800
	s_addc_u32 s5, s5, 0
	s_sub_u32 s6, s4, 0x1800
	s_subb_u32 s7, s5, 0
	s_lshl_b32 s1, s0, 6
	s_add_u32 s10, s93, s1
	s_addc_u32 s11, s95, 0
	global_load_dwordx4 v[0:3], v60, s[2:3]
	global_load_dwordx2 v[4:5], v61, s[4:5] offset:2048
	global_load_dwordx2 v[6:7], v61, s[6:7] offset:2048
	global_load_dwordx2 v[8:9], v61, s[8:9]
	global_load_dword v10, v62, s[10:11]
.Lp4_loop:
	s_and_b32 s0, s12, 0x3ffc
	s_cmp_eq_u32 s0, 0
	s_cselect_b32 s13, 0, -1
	s_mov_b64 vcc, s[8:9]
	s_add_i32 s12, s12, s94
	s_cmpk_gt_i32 s12, 0x7fff
	s_cbranch_scc1 .Lp4_lastA
	s_ashr_i32 s0, s12, 2
	s_lshl_b32 s1, s0, 12
	s_add_u32 s2, s88, 0x7b00000
	s_addc_u32 s3, s89, 0
	s_add_u32 s2, s2, s1
	s_addc_u32 s3, s3, 0
	s_add_u32 s8, s60, s1
	s_addc_u32 s9, s61, 0
	s_mul_i32 s1, s0, 0x1800
	s_add_u32 s4, s50, s1
	s_addc_u32 s5, s51, 0
	s_add_u32 s4, s4, 0x800
	s_addc_u32 s5, s5, 0
	s_sub_u32 s6, s4, 0x1800
	s_subb_u32 s7, s5, 0
	s_lshl_b32 s1, s0, 6
	s_add_u32 s10, s93, s1
	s_addc_u32 s11, s95, 0
	global_load_dwordx4 v[12:15], v60, s[2:3]
	global_load_dwordx2 v[16:17], v61, s[4:5] offset:2048
	global_load_dwordx2 v[18:19], v61, s[6:7] offset:2048
	global_load_dwordx2 v[20:21], v61, s[8:9]
	global_load_dword v22, v62, s[10:11]
	s_waitcnt vmcnt(9)
	v_mov_b32_e32 v32, v1
	v_mov_b32_e32 v33, v2
	v_mov_b32_e32 v34, v0
	v_mov_b32_e32 v35, v3
	v_pk_add_f32 v[32:33], v[32:33], v[34:35]
	s_nop 0
	v_add_f32_e32 v36, v32, v33
	s_nop 1
	v_add_f32_dpp v36, v36, v36 row_ror:8 row_mask:0xf bank_mask:0xf bound_ctrl:1
	s_nop 1
	v_add_f32_dpp v36, v36, v36 row_ror:4 row_mask:0xf bank_mask:0xf bound_ctrl:1
	s_nop 1
	v_add_f32_dpp v36, v36, v36 row_ror:2 row_mask:0xf bank_mask:0xf bound_ctrl:1
	s_nop 1
	v_add_f32_dpp v36, v36, v36 row_ror:1 row_mask:0xf bank_mask:0xf bound_ctrl:1
	v_fmamk_f32 v3, v36, 0xbc800000, v3
	v_fmamk_f32 v2, v36, 0xbc800000, v2
	v_fmamk_f32 v1, v36, 0xbc800000, v1
	v_fmac_f32_e32 v0, 0xbc800000, v36
	v_pk_mul_f32 v[32:33], v[2:3], v[2:3]
	v_pk_mul_f32 v[34:35], v[0:1], v[0:1]
	s_nop 0
	v_pk_mov_b32 v[38:39], v[34:35], v[32:33] op_sel:[1,0]
	v_mov_b32_e32 v35, v33
	v_pk_add_f32 v[32:33], v[38:39], v[34:35]
	s_nop 0
	v_add_f32_e32 v36, v32, v33
	s_nop 1
	v_add_f32_dpp v36, v36, v36 row_ror:8 row_mask:0xf bank_mask:0xf bound_ctrl:1
	s_nop 1
	v_add_f32_dpp v36, v36, v36 row_ror:4 row_mask:0xf bank_mask:0xf bound_ctrl:1
	s_nop 1
	v_add_f32_dpp v36, v36, v36 row_ror:2 row_mask:0xf bank_mask:0xf bound_ctrl:1
	s_nop 1
	v_mov_b32_dpp v37, v36 row_ror:1 row_mask:0xf bank_mask:0xf
	s_nop 0
	v_add_f32_e32 v36, v36, v37
	v_fmamk_f32 v36, v36, 0x3c800000, v76
	v_rsq_f32_e32 v40, v36
	s_waitcnt vmcnt(7)
	v_lshlrev_b32_e32 v42, 16, v4
	v_and_b32_e32 v43, 0xffff0000, v4
	v_lshlrev_b32_e32 v44, 16, v5
	v_and_b32_e32 v45, 0xffff0000, v5
	v_and_b32_e32 v6, s13, v6
	v_and_b32_e32 v7, s13, v7
	v_lshlrev_b32_e32 v46, 16, v6
	v_and_b32_e32 v47, 0xffff0000, v6
	v_lshlrev_b32_e32 v48, 16, v7
	v_and_b32_e32 v49, 0xffff0000, v7
	v_sub_f32_e32 v46, v46, v42
	v_sub_f32_e32 v47, v47, v43
	v_sub_f32_e32 v48, v48, v44
	v_sub_f32_e32 v49, v49, v45
	v_pk_mul_f32 v[2:3], v[2:3], v[40:41] op_sel_hi:[1,0]
	v_pk_mul_f32 v[0:1], v[0:1], v[40:41] op_sel_hi:[1,0]
	v_pk_fma_f32 v[2:3], v[66:67], v[2:3], v[70:71]
	v_pk_fma_f32 v[0:1], v[64:65], v[0:1], v[68:69]
	v_pk_fma_f32 v[48:49], v[48:49], v[74:75], v[44:45]
	v_pk_fma_f32 v[46:47], v[46:47], v[72:73], v[42:43]
	s_waitcnt vmcnt(6)
	v_lshlrev_b32_e32 v50, 16, v8
	v_and_b32_e32 v51, 0xffff0000, v8
	v_lshlrev_b32_e32 v52, 16, v9
	v_and_b32_e32 v53, 0xffff0000, v9
	s_waitcnt vmcnt(5)
	v_mov_b32_e32 v54, v10
	v_pk_fma_f32 v[2:3], v[48:49], v[54:55], v[2:3] op_sel_hi:[1,0,1]
	v_pk_fma_f32 v[0:1], v[46:47], v[54:55], v[0:1] op_sel_hi:[1,0,1]
	v_pk_mul_f32 v[2:3], v[2:3], v[52:53]
	v_pk_mul_f32 v[0:1], v[0:1], v[50:51]
	s_nop 0
	v_cvt_pk_bf16_f32 v0, v0, v1
	v_cvt_pk_bf16_f32 v1, v2, v3
	global_store_dwordx2 v61, v[0:1], vcc
	s_and_b32 s0, s12, 0x3ffc
	s_cmp_eq_u32 s0, 0
	s_cselect_b32 s13, 0, -1
	s_mov_b64 vcc, s[8:9]
	s_add_i32 s12, s12, s94
	s_cmpk_gt_i32 s12, 0x7fff
	s_cbranch_scc1 .Lp4_lastB
; DI unsigned pk2(float lo, float hi) { const f32x2 v = {lo, hi}; const bf16x2_t b = __builtin_convertvector(v, bf16x2_t); return __builtin_bit_cast(unsigned, b); }
; DI f32x4 ldbf4(const u16* p) { const u32x2 v = *(const u32x2*)p; return (f32x4){bf2f(v.x & 0xffffu), bf2f(v.x >> 16), bf2f(v.y & 0xffffu), bf2f(v.y >> 16)}; }
; #define ROW_ALLSUM4(v) do { v += DPPF4(v, 0x128); v += DPPF4(v, 0x124); v += DPPF4(v, 0x122); v += DPPF4(v, 0x121); } while (0)
; __global__ void __launch_bounds__(512, 2) fwd_megakernel(Args a) {
;     ...
;         for (int it = gw; it < M * NH / 4; it += NGW) {
;             const int mh = it * 4 + (lane >> 4), m = mh >> 4, h = mh & 15, c = h * 64 + 4 * (lane & 15);
;             const f32x4 y = *(const f32x4*)(yraw + (size_t)m * RW + c);
;             float sm = (y.x + y.y) + (y.z + y.w); ROW_ALLSUM4(sm);
;             const float mu = sm * (1.f / 64.f); const f32x4 d = y - mu;
;             float sq = (d.x * d.x + d.y * d.y) + (d.z * d.z + d.w * d.w); ROW_ALLSUM4(sq);
;             const f32x4 yn = d * __builtin_amdgcn_rsqf(sq * (1.f / 64.f) + GN_EPS) * *(const f32x4*)(gn_w + c) + *(const f32x4*)(gn_b + c);
;             const f32x4 v = ldbf4(P + (size_t)m * RPROJ + 2048 + c);
;             const f32x4 vp = ((m & (SEQ - 1)) != 0) ? ldbf4(P + (size_t)(m - 1) * RPROJ + 2048 + c) : (f32x4){0.f, 0.f, 0.f, 0.f};
;             const f32x4 vs = v + (vp - v) * *(const f32x4*)(shift_mix + 2048 + c);
;             u32x2* p = (u32x2*)(SG + (size_t)m * 2048 + c); const u32x2 g2 = *p;
;             const f32x4 o = (yn + bonus[(size_t)m * NH + h] * vs) * (f32x4){bf2f(g2.x & 0xffffu), bf2f(g2.x >> 16), bf2f(g2.y & 0xffffu), bf2f(g2.y >> 16)};
;             u32x2 w; w.x = pk2(o.x, o.y); w.y = pk2(o.z, o.w); *p = w;
	s_ashr_i32 s0, s12, 2
	s_lshl_b32 s1, s0, 12
	s_add_u32 s2, s88, 0x7b00000
	s_addc_u32 s3, s89, 0
	s_add_u32 s2, s2, s1
	s_addc_u32 s3, s3, 0
	s_add_u32 s8, s60, s1
	s_addc_u32 s9, s61, 0
	s_mul_i32 s1, s0, 0x1800
	s_add_u32 s4, s50, s1
	s_addc_u32 s5, s51, 0
	s_add_u32 s4, s4, 0x800
	s_addc_u32 s5, s5, 0
	s_sub_u32 s6, s4, 0x1800
	s_subb_u32 s7, s5, 0
	s_lshl_b32 s1, s0, 6
	s_add_u32 s10, s93, s1
	s_addc_u32 s11, s95, 0
	global_load_dwordx4 v[0:3], v60, s[2:3]
	global_load_dwordx2 v[4:5], v61, s[4:5] offset:2048
	global_load_dwordx2 v[6:7], v61, s[6:7] offset:2048
	global_load_dwordx2 v[8:9], v61, s[8:9]
	global_load_dword v10, v62, s[10:11]
	s_waitcnt vmcnt(9)
	v_mov_b32_e32 v32, v13
	v_mov_b32_e32 v33, v14
	v_mov_b32_e32 v34, v12
	v_mov_b32_e32 v35, v15
	v_pk_add_f32 v[32:33], v[32:33], v[34:35]
	s_nop 0
	v_add_f32_e32 v36, v32, v33
	s_nop 1
	v_add_f32_dpp v36, v36, v36 row_ror:8 row_mask:0xf bank_mask:0xf bound_ctrl:1
	s_nop 1
	v_add_f32_dpp v36, v36, v36 row_ror:4 row_mask:0xf bank_mask:0xf bound_ctrl:1
	s_nop 1
	v_add_f32_dpp v36, v36, v36 row_ror:2 row_mask:0xf bank_mask:0xf bound_ctrl:1
	s_nop 1
	v_add_f32_dpp v36, v36, v36 row_ror:1 row_mask:0xf bank_mask:0xf bound_ctrl:1
	v_fmamk_f32 v15, v36, 0xbc800000, v15
	v_fmamk_f32 v14, v36, 0xbc800000, v14
	v_fmamk_f32 v13, v36, 0xbc800000, v13
	v_fmac_f32_e32 v12, 0xbc800000, v36
	v_pk_mul_f32 v[32:33], v[14:15], v[14:15]
	v_pk_mul_f32 v[34:35], v[12:13], v[12:13]
	s_nop 0
	v_pk_mov_b32 v[38:39], v[34:35], v[32:33] op_sel:[1,0]
	v_mov_b32_e32 v35, v33
	v_pk_add_f32 v[32:33], v[38:39], v[34:35]
	s_nop 0
	v_add_f32_e32 v36, v32, v33
	s_nop 1
	v_add_f32_dpp v36, v36, v36 row_ror:8 row_mask:0xf bank_mask:0xf bound_ctrl:1
	s_nop 1
	v_add_f32_dpp v36, v36, v36 row_ror:4 row_mask:0xf bank_mask:0xf bound_ctrl:1
	s_nop 1
	v_add_f32_dpp v36, v36, v36 row_ror:2 row_mask:0xf bank_mask:0xf bound_ctrl:1
	s_nop 1
	v_mov_b32_dpp v37, v36 row_ror:1 row_mask:0xf bank_mask:0xf
	s_nop 0
	v_add_f32_e32 v36, v36, v37
	v_fmamk_f32 v36, v36, 0x3c800000, v76
	v_rsq_f32_e32 v40, v36
	s_waitcnt vmcnt(7)
	v_lshlrev_b32_e32 v42, 16, v16
	v_and_b32_e32 v43, 0xffff0000, v16
	v_lshlrev_b32_e32 v44, 16, v17
	v_and_b32_e32 v45, 0xffff0000, v17
	v_and_b32_e32 v18, s13, v18
	v_and_b32_e32 v19, s13, v19
	v_lshlrev_b32_e32 v46, 16, v18
	v_and_b32_e32 v47, 0xffff0000, v18
	v_lshlrev_b32_e32 v48, 16, v19
	v_and_b32_e32 v49, 0xffff0000, v19
	v_sub_f32_e32 v46, v46, v42
	v_sub_f32_e32 v47, v47, v43
	v_sub_f32_e32 v48, v48, v44
	v_sub_f32_e32 v49, v49, v45
	v_pk_mul_f32 v[14:15], v[14:15], v[40:41] op_sel_hi:[1,0]
	v_pk_mul_f32 v[12:13], v[12:13], v[40:41] op_sel_hi:[1,0]
	v_pk_fma_f32 v[14:15], v[66:67], v[14:15], v[70:71]
	v_pk_fma_f32 v[12:13], v[64:65], v[12:13], v[68:69]
	v_pk_fma_f32 v[48:49], v[48:49], v[74:75], v[44:45]
	v_pk_fma_f32 v[46:47], v[46:47], v[72:73], v[42:43]
	s_waitcnt vmcnt(6)
	v_lshlrev_b32_e32 v50, 16, v20
	v_and_b32_e32 v51, 0xffff0000, v20
	v_lshlrev_b32_e32 v52, 16, v21
	v_and_b32_e32 v53, 0xffff0000, v21
	s_waitcnt vmcnt(5)
	v_mov_b32_e32 v54, v22
	v_pk_fma_f32 v[14:15], v[48:49], v[54:55], v[14:15] op_sel_hi:[1,0,1]
	v_pk_fma_f32 v[12:13], v[46:47], v[54:55], v[12:13] op_sel_hi:[1,0,1]
	v_pk_mul_f32 v[14:15], v[14:15], v[52:53]
	v_pk_mul_f32 v[12:13], v[12:13], v[50:51]
	s_nop 0
	v_cvt_pk_bf16_f32 v12, v12, v13
	v_cvt_pk_bf16_f32 v13, v14, v15
	global_store_dwordx2 v61, v[12:13], vcc
	s_branch .Lp4_loop
; DI unsigned pk2(float lo, float hi) { const f32x2 v = {lo, hi}; const bf16x2_t b = __builtin_convertvector(v, bf16x2_t); return __builtin_bit_cast(unsigned, b); }
; DI f32x4 ldbf4(const u16* p) { const u32x2 v = *(const u32x2*)p; return (f32x4){bf2f(v.x & 0xffffu), bf2f(v.x >> 16), bf2f(v.y & 0xffffu), bf2f(v.y >> 16)}; }
; #define ROW_ALLSUM4(v) do { v += DPPF4(v, 0x128); v += DPPF4(v, 0x124); v += DPPF4(v, 0x122); v += DPPF4(v, 0x121); } while (0)
; __global__ void __launch_bounds__(512, 2) fwd_megakernel(Args a) {
;     ...
;             const int mh = it * 4 + (lane >> 4), m = mh >> 4, h = mh & 15, c = h * 64 + 4 * (lane & 15);
;             const f32x4 y = *(const f32x4*)(yraw + (size_t)m * RW + c);
;             float sm = (y.x + y.y) + (y.z + y.w); ROW_ALLSUM4(sm);
;             const float mu = sm * (1.f / 64.f); const f32x4 d = y - mu;
;             float sq = (d.x * d.x + d.y * d.y) + (d.z * d.z + d.w * d.w); ROW_ALLSUM4(sq);
;             const f32x4 yn = d * __builtin_amdgcn_rsqf(sq * (1.f / 64.f) + GN_EPS) * *(const f32x4*)(gn_w + c) + *(const f32x4*)(gn_b + c);
;             const f32x4 v = ldbf4(P + (size_t)m * RPROJ + 2048 + c);
;             const f32x4 vp = ((m & (SEQ - 1)) != 0) ? ldbf4(P + (size_t)(m - 1) * RPROJ + 2048 + c) : (f32x4){0.f, 0.f, 0.f, 0.f};
;             const f32x4 vs = v + (vp - v) * *(const f32x4*)(shift_mix + 2048 + c);
;             u32x2* p = (u32x2*)(SG + (size_t)m * 2048 + c); const u32x2 g2 = *p;
;             const f32x4 o = (yn + bonus[(size_t)m * NH + h] * vs) * (f32x4){bf2f(g2.x & 0xffffu), bf2f(g2.x >> 16), bf2f(g2.y & 0xffffu), bf2f(g2.y >> 16)};
;             u32x2 w; w.x = pk2(o.x, o.y); w.y = pk2(o.z, o.w); *p = w;
.Lp4_lastA:
	s_waitcnt vmcnt(4)
	v_mov_b32_e32 v32, v1
	v_mov_b32_e32 v33, v2
	v_mov_b32_e32 v34, v0
	v_mov_b32_e32 v35, v3
	v_pk_add_f32 v[32:33], v[32:33], v[34:35]
	s_nop 0
	v_add_f32_e32 v36, v32, v33
	s_nop 1
	v_add_f32_dpp v36, v36, v36 row_ror:8 row_mask:0xf bank_mask:0xf bound_ctrl:1
	s_nop 1
	v_add_f32_dpp v36, v36, v36 row_ror:4 row_mask:0xf bank_mask:0xf bound_ctrl:1
	s_nop 1
	v_add_f32_dpp v36, v36, v36 row_ror:2 row_mask:0xf bank_mask:0xf bound_ctrl:1
	s_nop 1
	v_add_f32_dpp v36, v36, v36 row_ror:1 row_mask:0xf bank_mask:0xf bound_ctrl:1
	v_fmamk_f32 v3, v36, 0xbc800000, v3
	v_fmamk_f32 v2, v36, 0xbc800000, v2
	v_fmamk_f32 v1, v36, 0xbc800000, v1
	v_fmac_f32_e32 v0, 0xbc800000, v36
	v_pk_mul_f32 v[32:33], v[2:3], v[2:3]
	v_pk_mul_f32 v[34:35], v[0:1], v[0:1]
	s_nop 0
	v_pk_mov_b32 v[38:39], v[34:35], v[32:33] op_sel:[1,0]
	v_mov_b32_e32 v35, v33
	v_pk_add_f32 v[32:33], v[38:39], v[34:35]
	s_nop 0
	v_add_f32_e32 v36, v32, v33
	s_nop 1
	v_add_f32_dpp v36, v36, v36 row_ror:8 row_mask:0xf bank_mask:0xf bound_ctrl:1
	s_nop 1
	v_add_f32_dpp v36, v36, v36 row_ror:4 row_mask:0xf bank_mask:0xf bound_ctrl:1
	s_nop 1
	v_add_f32_dpp v36, v36, v36 row_ror:2 row_mask:0xf bank_mask:0xf bound_ctrl:1
	s_nop 1
	v_mov_b32_dpp v37, v36 row_ror:1 row_mask:0xf bank_mask:0xf
	s_nop 0
	v_add_f32_e32 v36, v36, v37
	v_fmamk_f32 v36, v36, 0x3c800000, v76
	v_rsq_f32_e32 v40, v36
	s_waitcnt vmcnt(2)
	v_lshlrev_b32_e32 v42, 16, v4
	v_and_b32_e32 v43, 0xffff0000, v4
	v_lshlrev_b32_e32 v44, 16, v5
	v_and_b32_e32 v45, 0xffff0000, v5
	v_and_b32_e32 v6, s13, v6
	v_and_b32_e32 v7, s13, v7
	v_lshlrev_b32_e32 v46, 16, v6
	v_and_b32_e32 v47, 0xffff0000, v6
	v_lshlrev_b32_e32 v48, 16, v7
	v_and_b32_e32 v49, 0xffff0000, v7
	v_sub_f32_e32 v46, v46, v42
	v_sub_f32_e32 v47, v47, v43
	v_sub_f32_e32 v48, v48, v44
	v_sub_f32_e32 v49, v49, v45
	v_pk_mul_f32 v[2:3], v[2:3], v[40:41] op_sel_hi:[1,0]
	v_pk_mul_f32 v[0:1], v[0:1], v[40:41] op_sel_hi:[1,0]
	v_pk_fma_f32 v[2:3], v[66:67], v[2:3], v[70:71]
	v_pk_fma_f32 v[0:1], v[64:65], v[0:1], v[68:69]
	v_pk_fma_f32 v[48:49], v[48:49], v[74:75], v[44:45]
	v_pk_fma_f32 v[46:47], v[46:47], v[72:73], v[42:43]
	s_waitcnt vmcnt(1)
	v_lshlrev_b32_e32 v50, 16, v8
	v_and_b32_e32 v51, 0xffff0000, v8
	v_lshlrev_b32_e32 v52, 16, v9
	v_and_b32_e32 v53, 0xffff0000, v9
	s_waitcnt vmcnt(0)
	v_mov_b32_e32 v54, v10
	v_pk_fma_f32 v[2:3], v[48:49], v[54:55], v[2:3] op_sel_hi:[1,0,1]
	v_pk_fma_f32 v[0:1], v[46:47], v[54:55], v[0:1] op_sel_hi:[1,0,1]
	v_pk_mul_f32 v[2:3], v[2:3], v[52:53]
	v_pk_mul_f32 v[0:1], v[0:1], v[50:51]
	s_nop 0
	v_cvt_pk_bf16_f32 v0, v0, v1
	v_cvt_pk_bf16_f32 v1, v2, v3
	global_store_dwordx2 v61, v[0:1], vcc
	s_branch .LBB0_538
.Lp4_lastB:
	s_waitcnt vmcnt(4)
	v_mov_b32_e32 v32, v13
	v_mov_b32_e32 v33, v14
	v_mov_b32_e32 v34, v12
	v_mov_b32_e32 v35, v15
	v_pk_add_f32 v[32:33], v[32:33], v[34:35]
	s_nop 0
	v_add_f32_e32 v36, v32, v33
	s_nop 1
	v_add_f32_dpp v36, v36, v36 row_ror:8 row_mask:0xf bank_mask:0xf bound_ctrl:1
	s_nop 1
	v_add_f32_dpp v36, v36, v36 row_ror:4 row_mask:0xf bank_mask:0xf bound_ctrl:1
	s_nop 1
	v_add_f32_dpp v36, v36, v36 row_ror:2 row_mask:0xf bank_mask:0xf bound_ctrl:1
	s_nop 1
	v_add_f32_dpp v36, v36, v36 row_ror:1 row_mask:0xf bank_mask:0xf bound_ctrl:1
	v_fmamk_f32 v15, v36, 0xbc800000, v15
	v_fmamk_f32 v14, v36, 0xbc800000, v14
	v_fmamk_f32 v13, v36, 0xbc800000, v13
	v_fmac_f32_e32 v12, 0xbc800000, v36
	v_pk_mul_f32 v[32:33], v[14:15], v[14:15]
	v_pk_mul_f32 v[34:35], v[12:13], v[12:13]
	s_nop 0
	v_pk_mov_b32 v[38:39], v[34:35], v[32:33] op_sel:[1,0]
	v_mov_b32_e32 v35, v33
	v_pk_add_f32 v[32:33], v[38:39], v[34:35]
	s_nop 0
	v_add_f32_e32 v36, v32, v33
	s_nop 1
	v_add_f32_dpp v36, v36, v36 row_ror:8 row_mask:0xf bank_mask:0xf bound_ctrl:1
	s_nop 1
	v_add_f32_dpp v36, v36, v36 row_ror:4 row_mask:0xf bank_mask:0xf bound_ctrl:1
	s_nop 1
	v_add_f32_dpp v36, v36, v36 row_ror:2 row_mask:0xf bank_mask:0xf bound_ctrl:1
	s_nop 1
	v_mov_b32_dpp v37, v36 row_ror:1 row_mask:0xf bank_mask:0xf
	s_nop 0
	v_add_f32_e32 v36, v36, v37
	v_fmamk_f32 v36, v36, 0x3c800000, v76
	v_rsq_f32_e32 v40, v36
	s_waitcnt vmcnt(2)
	v_lshlrev_b32_e32 v42, 16, v16
	v_and_b32_e32 v43, 0xffff0000, v16
	v_lshlrev_b32_e32 v44, 16, v17
	v_and_b32_e32 v45, 0xffff0000, v17
	v_and_b32_e32 v18, s13, v18
	v_and_b32_e32 v19, s13, v19
	v_lshlrev_b32_e32 v46, 16, v18
	v_and_b32_e32 v47, 0xffff0000, v18
	v_lshlrev_b32_e32 v48, 16, v19
	v_and_b32_e32 v49, 0xffff0000, v19
	v_sub_f32_e32 v46, v46, v42
	v_sub_f32_e32 v47, v47, v43
	v_sub_f32_e32 v48, v48, v44
	v_sub_f32_e32 v49, v49, v45
	v_pk_mul_f32 v[14:15], v[14:15], v[40:41] op_sel_hi:[1,0]
	v_pk_mul_f32 v[12:13], v[12:13], v[40:41] op_sel_hi:[1,0]
	v_pk_fma_f32 v[14:15], v[66:67], v[14:15], v[70:71]
	v_pk_fma_f32 v[12:13], v[64:65], v[12:13], v[68:69]
	v_pk_fma_f32 v[48:49], v[48:49], v[74:75], v[44:45]
	v_pk_fma_f32 v[46:47], v[46:47], v[72:73], v[42:43]
	s_waitcnt vmcnt(1)
	v_lshlrev_b32_e32 v50, 16, v20
	v_and_b32_e32 v51, 0xffff0000, v20
	v_lshlrev_b32_e32 v52, 16, v21
	v_and_b32_e32 v53, 0xffff0000, v21
	s_waitcnt vmcnt(0)
	v_mov_b32_e32 v54, v22
	v_pk_fma_f32 v[14:15], v[48:49], v[54:55], v[14:15] op_sel_hi:[1,0,1]
	v_pk_fma_f32 v[12:13], v[46:47], v[54:55], v[12:13] op_sel_hi:[1,0,1]
	v_pk_mul_f32 v[14:15], v[14:15], v[52:53]
	v_pk_mul_f32 v[12:13], v[12:13], v[50:51]
	s_nop 0
	v_cvt_pk_bf16_f32 v12, v12, v13
	v_cvt_pk_bf16_f32 v13, v14, v15
	global_store_dwordx2 v61, v[12:13], vcc
	s_branch .LBB0_538
